# FFN-up tile loop: next-unit (pm,pn) decode without the float-reciprocal division (group size is always 8)
# baseline (speedup 1.0000x reference)
.LBB0_737:
	s_add_i32 s79, s79, 1
	s_mul_i32 s6, s79, s20
	s_mul_hi_u32 s7, s79, s14
	s_add_i32 s7, s7, s6
	s_mul_i32 s6, s79, s14
	s_add_u32 s42, s6, s2
	s_addc_u32 s43, s7, s71
	v_mov_b64_e32 v[0:1], 0xb00
	v_cmp_lt_i64_e64 s[6:7], s[42:43], v[0:1]
	v_mov_b64_e32 v[0:1], 0xaff
	v_cmp_gt_i64_e32 vcc, s[42:43], v[0:1]
	s_cbranch_vccnz .LBB0_739
	s_ashr_i32 s18, s42, 31
	s_lshr_b32 s18, s18, 29
	s_add_i32 s18, s42, s18
	s_ashr_i32 s19, s18, 3
	s_and_b32 s18, s18, -8
	s_sub_i32 s18, s42, s18
	s_cmp_lt_i32 s18, 0
	s_movk_i32 s30, 0x161
	s_cselect_b32 s30, s30, 0x160
	s_mul_i32 s18, s18, s30
	s_add_i32 s18, s18, s19
	s_mul_hi_i32 s19, s18, 0x2e8ba2e9
	s_lshr_b32 s30, s19, 31
	s_ashr_i32 s19, s19, 5
	s_add_i32 s19, s19, s30
	s_lshl_b32 s31, s19, 3
	s_mulk_i32 s19, 0xb0
	s_sub_i32 s18, s18, s19
	s_lshr_b32 s30, s18, 3
	s_and_b32 s18, s18, 7
	s_add_i32 s58, s31, s18
